# full stack of bit-identical edits: RWKV P6 interleaved reductions + packed transposed stores, NSA QK reads ahead of the MFMA chain + permlane32_swap max exchange, on top of the 1.032x version
# speedup vs baseline: 1.0017x; 1.0017x over previous
; DI float shfl_xor_(float v, int mask, int lane) { return __int_as_float(__builtin_amdgcn_ds_bpermute((lane ^ mask) << 2, __float_as_int(v))); }
; #define MFMA32(a, b, c) __builtin_amdgcn_mfma_f32_32x32x16_bf16((a), (b), (c), 0, 0, 0)
; DI void flash_update(FlashState& st, f32x16& sc0, f32x16& sc1, const bf16_t* VT, int vs, int qi, int hl) {
;     const bf16x8 va0 = ld_vfrag(VT, qi * vs + 4 * hl), vb0 = ld_vfrag(VT, (32 + qi) * vs + 4 * hl);
;     const bf16x8 va1 = ld_vfrag(VT, qi * vs + 32 + 4 * hl), vb1 = ld_vfrag(VT, (32 + qi) * vs + 32 + 4 * hl);
;     asm volatile("" ::: "memory");
;     float mt = -INFINITY;
; #pragma unroll
;     for (int i = 0; i < 16; ++i) mt = fmaxf(mt, fmaxf(sc0[i], sc1[i]));
;     mt = fmaxf(mt, shfl_xor_(mt, 32, qi + 32 * hl));
;     const float mnew = fmaxf(st.m, mt), muse = (mnew == -INFINITY) ? 0.f : mnew;
;     const float alpha = __builtin_amdgcn_exp2f(st.m - muse);
;     float ls = 0.f;
; #pragma unroll
;     for (int i = 0; i < 16; ++i) { sc0[i] = __builtin_amdgcn_exp2f(sc0[i] - muse); sc1[i] = __builtin_amdgcn_exp2f(sc1[i] - muse); ls += sc0[i] + sc1[i]; }
;     st.l = st.l * alpha + ls; st.m = mnew;
;     st.o0 *= alpha; st.o1 *= alpha;
;     {
;         const bf16x8 p0 = pack8(sc0[0], sc0[1], sc0[2], sc0[3], sc0[4], sc0[5], sc0[6], sc0[7]);
;         const bf16x8 p1 = pack8(sc1[0], sc1[1], sc1[2], sc1[3], sc1[4], sc1[5], sc1[6], sc1[7]);
;         const bf16x8 wa0 = ld_vfrag(VT, qi * vs + 16 + 4 * hl), wb0 = ld_vfrag(VT, (32 + qi) * vs + 16 + 4 * hl);
;         const bf16x8 wa1 = ld_vfrag(VT, qi * vs + 48 + 4 * hl), wb1 = ld_vfrag(VT, (32 + qi) * vs + 48 + 4 * hl);
;         st.o0 = MFMA32(va0, p0, st.o0); st.o1 = MFMA32(vb0, p0, st.o1); st.o0 = MFMA32(va1, p1, st.o0); st.o1 = MFMA32(vb1, p1, st.o1);
.LBB0_781:
	s_or_b64 exec, exec, s[10:11]
	v_max_f32_e32 v0, v34, v34
	s_nop 4
	v_max_f32_e32 v66, v50, v50
	v_max_f32_e32 v0, v66, v0
	v_max_f32_e32 v66, v35, v35
	v_max_f32_e32 v67, v51, v51
	v_max_f32_e32 v66, v67, v66
	s_mov_b32 s0, 0xff800000
	v_max3_f32 v0, v0, s0, v66
	v_max_f32_e32 v66, v36, v36
	v_max_f32_e32 v67, v52, v52
	v_max_f32_e32 v66, v67, v66
	v_max_f32_e32 v67, v37, v37
	v_max_f32_e32 v68, v53, v53
	v_max_f32_e32 v67, v68, v67
	v_max3_f32 v0, v0, v66, v67
	v_max_f32_e32 v66, v38, v38
	v_max_f32_e32 v67, v54, v54
	v_max_f32_e32 v66, v67, v66
	v_max_f32_e32 v67, v39, v39
	v_max_f32_e32 v68, v55, v55
	v_max_f32_e32 v67, v68, v67
	v_max3_f32 v0, v0, v66, v67
	v_max_f32_e32 v66, v40, v40
	v_max_f32_e32 v67, v56, v56
	v_max_f32_e32 v66, v67, v66
	v_max_f32_e32 v67, v41, v41
	v_max_f32_e32 v68, v57, v57
	v_max_f32_e32 v67, v68, v67
	v_max3_f32 v0, v0, v66, v67
	v_max_f32_e32 v66, v42, v42
	v_max_f32_e32 v67, v58, v58
	v_max_f32_e32 v66, v67, v66
	v_max_f32_e32 v67, v43, v43
	v_max_f32_e32 v68, v59, v59
	v_max_f32_e32 v67, v68, v67
	v_max3_f32 v0, v0, v66, v67
	v_max_f32_e32 v66, v44, v44
	v_max_f32_e32 v67, v60, v60
	v_max_f32_e32 v66, v67, v66
	v_max_f32_e32 v67, v45, v45
	v_max_f32_e32 v68, v61, v61
	v_max_f32_e32 v67, v68, v67
	v_max3_f32 v0, v0, v66, v67
	v_max_f32_e32 v66, v46, v46
	v_max_f32_e32 v67, v62, v62
	v_max_f32_e32 v66, v67, v66
	v_max_f32_e32 v67, v47, v47
	v_max_f32_e32 v68, v63, v63
	v_max_f32_e32 v67, v68, v67
	v_max3_f32 v0, v0, v66, v67
	v_max_f32_e32 v66, v48, v48
	v_max_f32_e32 v67, v64, v64
	v_max_f32_e32 v66, v67, v66
	v_max_f32_e32 v67, v49, v49
	v_max_f32_e32 v68, v65, v65
	v_max_f32_e32 v67, v68, v67
	v_max3_f32 v0, v0, v66, v67
	v_mov_b32_e32 v192, v0
	v_mov_b32_e32 v193, v0
	v_add_u32_e32 v92, 0x2000, v147
	s_nop 0
	v_permlane32_swap_b32_e32 v192, v193
	v_max_f32_e32 v66, v192, v193
	s_waitcnt lgkmcnt(0)
	v_max3_f32 v85, v152, v0, v66
	v_cmp_neq_f32_e32 vcc, s0, v85
	s_nop 1
	v_cndmask_b32_e32 v88, 0, v85, vcc
	v_sub_f32_e32 v0, v50, v88
	v_exp_f32_e32 v89, v0
	v_sub_f32_e32 v0, v34, v88
	v_exp_f32_e32 v90, v0
	v_sub_f32_e32 v0, v51, v88
	v_exp_f32_e32 v74, v0
	v_sub_f32_e32 v0, v35, v88
	v_exp_f32_e32 v0, v0
	v_add_f32_e32 v75, v89, v90
	v_sub_f32_e32 v38, v38, v88
	v_sub_f32_e32 v47, v47, v88
	v_pk_add_f32 v[34:35], v[74:75], v[0:1]
	s_nop 0
	v_pk_add_f32 v[50:51], v[34:35], v[34:35] op_sel_hi:[0,1]
	v_sub_f32_e32 v34, v52, v88
	v_exp_f32_e32 v75, v34
	v_sub_f32_e32 v34, v36, v88
	v_exp_f32_e32 v91, v34
	v_sub_f32_e32 v34, v53, v88
	v_exp_f32_e32 v76, v34
	v_sub_f32_e32 v34, v37, v88
	v_exp_f32_e32 v50, v34
	v_add_f32_e32 v77, v75, v91
	ds_read2_b64 v[34:37], v92 offset0:128 offset1:130
	v_pk_add_f32 v[52:53], v[76:77], v[50:51]
	v_sub_f32_e32 v51, v54, v88
	v_exp_f32_e32 v77, v38
	v_sub_f32_e32 v38, v55, v88
	v_pk_add_f32 v[52:53], v[52:53], v[52:53] op_sel_hi:[0,1]
	v_exp_f32_e32 v51, v51
	v_exp_f32_e32 v78, v38
	v_sub_f32_e32 v38, v39, v88
	v_exp_f32_e32 v52, v38
	v_add_u32_e32 v38, v146, v139
	v_add_f32_e32 v79, v51, v77
	v_add_u32_e32 v93, 0x3000, v38
	v_pk_add_f32 v[38:39], v[78:79], v[52:53]
	s_nop 0
	v_pk_add_f32 v[80:81], v[38:39], v[38:39] op_sel_hi:[0,1]
	v_sub_f32_e32 v38, v56, v88
	v_exp_f32_e32 v53, v38
	v_sub_f32_e32 v38, v40, v88
	v_exp_f32_e32 v79, v38
	v_sub_f32_e32 v38, v57, v88
	v_exp_f32_e32 v82, v38
	v_sub_f32_e32 v38, v41, v88
	v_exp_f32_e32 v80, v38
	v_add_f32_e32 v83, v53, v79
	ds_read2_b64 v[54:57], v93 offset0:192 offset1:194
	ds_read2_b64 v[66:69], v92 offset0:136 offset1:138
	ds_read2_b64 v[70:73], v93 offset0:200 offset1:202
	v_pk_add_f32 v[38:39], v[82:83], v[80:81]
	s_nop 0
	v_pk_add_f32 v[38:39], v[38:39], v[38:39] op_sel_hi:[0,1]
	v_sub_f32_e32 v38, v58, v88
	v_exp_f32_e32 v81, v38
	v_sub_f32_e32 v38, v42, v88
	v_exp_f32_e32 v83, v38
	v_sub_f32_e32 v38, v59, v88
	v_exp_f32_e32 v58, v38
	v_sub_f32_e32 v38, v43, v88
	v_exp_f32_e32 v38, v38
	v_add_f32_e32 v59, v81, v83
	v_sub_f32_e32 v42, v152, v88
	v_exp_f32_e32 v84, v42
	v_pk_add_f32 v[40:41], v[58:59], v[38:39]
	v_sub_f32_e32 v39, v60, v88
	v_pk_add_f32 v[40:41], v[40:41], v[40:41] op_sel_hi:[0,1]
	v_sub_f32_e32 v40, v44, v88
	v_exp_f32_e32 v59, v40
	v_sub_f32_e32 v40, v61, v88
	v_exp_f32_e32 v39, v39
	v_exp_f32_e32 v60, v40
	v_sub_f32_e32 v40, v45, v88
	v_exp_f32_e32 v40, v40
	v_add_f32_e32 v61, v39, v59
	v_pk_mul_f32 v[32:33], v[32:33], v[84:85] op_sel_hi:[1,0]
	v_pk_mul_f32 v[30:31], v[30:31], v[84:85] op_sel_hi:[1,0]
	v_pk_add_f32 v[42:43], v[60:61], v[40:41]
	v_pk_mul_f32 v[28:29], v[28:29], v[84:85] op_sel_hi:[1,0]
	v_pk_add_f32 v[86:87], v[42:43], v[42:43] op_sel_hi:[0,1]
	v_pk_mul_f32 v[26:27], v[26:27], v[84:85] op_sel_hi:[1,0]
	v_pk_mul_f32 v[24:25], v[24:25], v[84:85] op_sel_hi:[1,0]
	v_pk_mul_f32 v[22:23], v[22:23], v[84:85] op_sel_hi:[1,0]
	v_pk_mul_f32 v[20:21], v[20:21], v[84:85] op_sel_hi:[1,0]
	v_pk_mul_f32 v[18:19], v[18:19], v[84:85] op_sel_hi:[1,0]
	v_pk_mul_f32 v[16:17], v[16:17], v[84:85] op_sel_hi:[1,0]
	v_cvt_pk_bf16_f32 v42, v89, v74
	v_cvt_pk_bf16_f32 v43, v75, v76
	v_cvt_pk_bf16_f32 v44, v51, v78
	v_cvt_pk_bf16_f32 v45, v53, v82
	v_pk_mul_f32 v[14:15], v[14:15], v[84:85] op_sel_hi:[1,0]
	v_pk_mul_f32 v[12:13], v[12:13], v[84:85] op_sel_hi:[1,0]
	v_pk_mul_f32 v[10:11], v[10:11], v[84:85] op_sel_hi:[1,0]
	v_pk_mul_f32 v[8:9], v[8:9], v[84:85] op_sel_hi:[1,0]
	v_pk_mul_f32 v[6:7], v[6:7], v[84:85] op_sel_hi:[1,0]
	v_pk_mul_f32 v[4:5], v[4:5], v[84:85] op_sel_hi:[1,0]
	v_pk_mul_f32 v[2:3], v[2:3], v[84:85] op_sel_hi:[1,0]
	s_waitcnt lgkmcnt(3)
; #define MFMA32(a, b, c) __builtin_amdgcn_mfma_f32_32x32x16_bf16((a), (b), (c), 0, 0, 0)
; DI void flash_update(FlashState& st, f32x16& sc0, f32x16& sc1, const bf16_t* VT, int vs, int qi, int hl) {
;     ...
;     for (int i = 0; i < 16; ++i) { sc0[i] = __builtin_amdgcn_exp2f(sc0[i] - muse); sc1[i] = __builtin_amdgcn_exp2f(sc1[i] - muse); ls += sc0[i] + sc1[i]; }
;     st.l = st.l * alpha + ls; st.m = mnew;
;     st.o0 *= alpha; st.o1 *= alpha;
;     {
;         const bf16x8 p0 = pack8(sc0[0], sc0[1], sc0[2], sc0[3], sc0[4], sc0[5], sc0[6], sc0[7]);
;         const bf16x8 p1 = pack8(sc1[0], sc1[1], sc1[2], sc1[3], sc1[4], sc1[5], sc1[6], sc1[7]);
;         const bf16x8 wa0 = ld_vfrag(VT, qi * vs + 16 + 4 * hl), wb0 = ld_vfrag(VT, (32 + qi) * vs + 16 + 4 * hl);
;         const bf16x8 wa1 = ld_vfrag(VT, qi * vs + 48 + 4 * hl), wb1 = ld_vfrag(VT, (32 + qi) * vs + 48 + 4 * hl);
;         st.o0 = MFMA32(va0, p0, st.o0); st.o1 = MFMA32(vb0, p0, st.o1); st.o0 = MFMA32(va1, p1, st.o0); st.o1 = MFMA32(vb1, p1, st.o1);
;         const bf16x8 r0 = pack8(sc0[8], sc0[9], sc0[10], sc0[11], sc0[12], sc0[13], sc0[14], sc0[15]);
;         const bf16x8 r1 = pack8(sc1[8], sc1[9], sc1[10], sc1[11], sc1[12], sc1[13], sc1[14], sc1[15]);
;         st.o0 = MFMA32(wa0, r0, st.o0); st.o1 = MFMA32(wb0, r0, st.o1); st.o0 = MFMA32(wa1, r1, st.o0); st.o1 = MFMA32(wb1, r1, st.o1);
	v_mfma_f32_32x32x16_bf16 v[18:33], v[34:37], v[42:45], v[18:33]
	v_sub_f32_e32 v34, v62, v88
	v_exp_f32_e32 v41, v34
	v_cvt_pk_bf16_f32 v34, v90, v0
	v_cvt_pk_bf16_f32 v35, v91, v50
	v_cvt_pk_bf16_f32 v36, v77, v52
	v_cvt_pk_bf16_f32 v37, v79, v80
	v_exp_f32_e32 v86, v47
	s_waitcnt lgkmcnt(2)
	v_mfma_f32_32x32x16_bf16 v[2:17], v[54:57], v[42:45], v[2:17]
	v_sub_f32_e32 v42, v46, v88
	v_exp_f32_e32 v0, v42
	v_sub_f32_e32 v42, v63, v88
	v_exp_f32_e32 v46, v42
	v_sub_f32_e32 v42, v64, v88
	v_exp_f32_e32 v55, v42
	ds_read2_b64 v[42:45], v92 offset0:132 offset1:134
	s_waitcnt lgkmcnt(2)
	v_mfma_f32_32x32x16_bf16 v[18:33], v[66:69], v[34:37], v[18:33]
	v_cvt_pk_bf16_f32 v50, v81, v58
	v_cvt_pk_bf16_f32 v51, v39, v60
	v_cvt_pk_bf16_f32 v52, v41, v46
	v_add_f32_e32 v47, v41, v0
	v_sub_f32_e32 v39, v48, v88
	v_exp_f32_e32 v48, v39
	v_mov_b32_e32 v152, v85
	s_waitcnt lgkmcnt(1)
	v_mfma_f32_32x32x16_bf16 v[2:17], v[70:73], v[34:37], v[2:17]
	v_sub_f32_e32 v34, v65, v88
	v_exp_f32_e32 v54, v34
	ds_read2_b64 v[34:37], v93 offset0:196 offset1:198
	v_cvt_pk_bf16_f32 v53, v55, v54
	v_add_f32_e32 v55, v55, v48
	s_waitcnt lgkmcnt(1)
	v_mfma_f32_32x32x16_bf16 v[18:33], v[42:45], v[50:53], v[18:33]
	v_add_f32_e64 v42, v46, v86
	v_add_f32_e64 v43, v47, v87
	v_add_f32_e64 v46, v42, v42
	v_add_f32_e64 v47, v42, v43
	ds_read2_b64 v[42:45], v92 offset0:140 offset1:142
	s_waitcnt lgkmcnt(1)
	v_mfma_f32_32x32x16_bf16 v[2:17], v[34:37], v[50:53], v[2:17]
	v_sub_f32_e32 v34, v49, v88
	v_exp_f32_e32 v46, v34
	v_cvt_pk_bf16_f32 v34, v83, v38
	v_cvt_pk_bf16_f32 v35, v59, v40
	ds_read2_b64 v[38:41], v93 offset0:204 offset1:206
	v_cvt_pk_bf16_f32 v36, v0, v86
	v_cvt_pk_bf16_f32 v37, v48, v46
	s_waitcnt lgkmcnt(1)
	s_nop 0
	v_mfma_f32_32x32x16_bf16 v[18:33], v[42:45], v[34:37], v[18:33]
	v_add_f32_e64 v42, v54, v46
	v_add_f32_e64 v43, v55, v47
	v_add_f32_e32 v0, v42, v43
	v_fmac_f32_e32 v0, v140, v84
	v_mov_b32_e32 v140, v0
	s_waitcnt lgkmcnt(0)
	v_mfma_f32_32x32x16_bf16 v[2:17], v[38:41], v[34:37], v[2:17]
